# grid barrier: last XCD leader bumps every XCD generation word directly (removes one relay hop for followers)
# speedup vs baseline: 1.0055x; 1.0055x over previous
; __device__ __forceinline__ unsigned xb_ld(unsigned* p)              { return __hip_atomic_load(p, __ATOMIC_RELAXED, __HIP_MEMORY_SCOPE_AGENT); }
; __device__ __forceinline__ unsigned xb_add(unsigned* p, unsigned v) { return __hip_atomic_fetch_add(p, v, __ATOMIC_RELAXED, __HIP_MEMORY_SCOPE_AGENT); }
; #define XB_SPIN(cond, bar) do { unsigned _sp = 0; while (cond) { __builtin_amdgcn_s_sleep(1); \
;     if ((++_sp & 255u) == 0u) { if (xb_ld(&(bar)[XB_TMO])) break; if (_sp > XB_SPIN_CAP) { atomicAdd(&(bar)[XB_TMO], 1u); break; } } } } while (0)
; __device__ __forceinline__ void xcd_barrier(const XcdBarrier& b) {
;     ...
;         const unsigned old = xb_add(&bar[XB_XSUB(b.x)], 1u);
;         const unsigned gen = old / nloc;
;         if (old + 1u == (gen + 1u) * nloc) {
;             __builtin_amdgcn_fence(__ATOMIC_RELEASE, "agent");
;             asm volatile("s_waitcnt vmcnt(0)" ::: "memory");
;             const unsigned og = xb_add(&bar[XB_TOP], 1u);
;             const unsigned tg = og / nx;
;             if (og + 1u == (tg + 1u) * nx) xb_add(&bar[XB_TOPGEN], 1u);
;             else XB_SPIN(xb_ld(&bar[XB_TOPGEN]) == tg, bar);
.LBB0_138:
	s_or_b64 exec, exec, s[12:13]
	v_cvt_f32_u32_e32 v0, v1
	s_waitcnt vmcnt(0)
	v_readfirstlane_b32 s0, v3
	v_sub_u32_e32 v3, 0, v1
	s_add_u32 s12, s4, 0x3500
	v_rcp_iflag_f32_e32 v0, v0
	v_add_u32_e32 v2, s0, v2
	v_add_u32_e32 v5, 1, v2
	s_addc_u32 s13, s5, 0
	v_mul_f32_e32 v0, 0x4f7ffffe, v0
	v_cvt_u32_f32_e32 v0, v0
	s_mov_b64 s[14:15], -1
	v_mul_lo_u32 v3, v3, v0
	v_mul_hi_u32 v3, v0, v3
	v_add_u32_e32 v0, v0, v3
	v_mul_hi_u32 v0, v2, v0
	v_mul_lo_u32 v3, v0, v1
	v_sub_u32_e32 v2, v2, v3
	v_add_u32_e32 v4, 1, v0
	v_cmp_ge_u32_e32 vcc, v2, v1
	v_sub_u32_e32 v3, v2, v1
	s_nop 0
	v_cndmask_b32_e32 v0, v0, v4, vcc
	v_cndmask_b32_e32 v2, v2, v3, vcc
	v_add_u32_e32 v3, 1, v0
	v_cmp_ge_u32_e32 vcc, v2, v1
	s_nop 1
	v_cndmask_b32_e32 v4, v0, v3, vcc
	v_mul_lo_u32 v0, v1, v4
	v_add_u32_e32 v0, v0, v1
	v_cmp_ne_u32_e32 vcc, v5, v0
	v_mov_b64_e32 v[2:3], s[12:13]
	s_and_b64 s[98:99], vcc, exec
	s_and_saveexec_b64 s[10:11], vcc
	s_cbranch_execz .LBB0_150
	v_mov_b32_e32 v1, 0
	global_load_dword v0, v1, s[12:13] sc1
	s_mov_b64 s[20:21], 0
	s_waitcnt vmcnt(0)
	v_cmp_eq_u32_e32 vcc, v0, v4
	s_and_saveexec_b64 s[16:17], vcc
	s_cbranch_execz .LBB0_149
	s_add_u32 s14, s4, 0x200
	s_addc_u32 s15, s5, 0
	s_mov_b32 s0, 1
	s_mov_b64 s[4:5], 0
	s_branch .LBB0_142

; __device__ __forceinline__ unsigned xb_ld(unsigned* p)              { return __hip_atomic_load(p, __ATOMIC_RELAXED, __HIP_MEMORY_SCOPE_AGENT); }
; __device__ __forceinline__ unsigned xb_add(unsigned* p, unsigned v) { return __hip_atomic_fetch_add(p, v, __ATOMIC_RELAXED, __HIP_MEMORY_SCOPE_AGENT); }
; #define XB_SPIN(cond, bar) do { unsigned _sp = 0; while (cond) { __builtin_amdgcn_s_sleep(1); \
;     if ((++_sp & 255u) == 0u) { if (xb_ld(&(bar)[XB_TMO])) break; if (_sp > XB_SPIN_CAP) { atomicAdd(&(bar)[XB_TMO], 1u); break; } } } } while (0)
; __device__ __forceinline__ void xcd_barrier(const XcdBarrier& b) {
;     ...
;             if (og + 1u == (tg + 1u) * nx) xb_add(&bar[XB_TOPGEN], 1u);
;             else XB_SPIN(xb_ld(&bar[XB_TOPGEN]) == tg, bar);
;             __builtin_amdgcn_fence(__ATOMIC_ACQUIRE, "agent");
;             xb_add(&bar[XB_XGEN(b.x)], 1u);
.LBB0_152:
	s_or_b64 exec, exec, s[4:5]
	s_cmp_eq_u64 s[98:99], 0
	s_cbranch_scc0 .Lxb_notlast_1
	v_mov_b32_e32 v2, 0x2400
	v_mov_b32_e32 v3, 1
	global_atomic_add v2, v3, s[96:97]
	global_atomic_add v2, v3, s[96:97] offset:256
	global_atomic_add v2, v3, s[96:97] offset:512
	global_atomic_add v2, v3, s[96:97] offset:768
	global_atomic_add v2, v3, s[96:97] offset:1024
	global_atomic_add v2, v3, s[96:97] offset:1280
	global_atomic_add v2, v3, s[96:97] offset:1536
	global_atomic_add v2, v3, s[96:97] offset:1792
	global_atomic_add v2, v3, s[96:97] offset:2048
	global_atomic_add v2, v3, s[96:97] offset:2304
	global_atomic_add v2, v3, s[96:97] offset:2560
	global_atomic_add v2, v3, s[96:97] offset:2816
	global_atomic_add v2, v3, s[96:97] offset:3072
	global_atomic_add v2, v3, s[96:97] offset:3328
	global_atomic_add v2, v3, s[96:97] offset:3584
	global_atomic_add v2, v3, s[96:97] offset:3840
.Lxb_notlast_1:
	s_mov_b64 s[4:5], exec
	v_mbcnt_lo_u32_b32 v0, s4, 0
	v_mbcnt_hi_u32_b32 v0, s5, v0
	v_cmp_eq_u32_e32 vcc, 0, v0
	s_waitcnt vmcnt(0) lgkmcnt(0)
	buffer_inv sc1
	s_and_saveexec_b64 s[10:11], vcc
	s_cbranch_execz .LBB0_154
	s_bcnt1_i32_b64 s0, s[4:5]
	v_mov_b32_e32 v0, 0x2000
	v_mov_b32_e32 v1, s0

; __device__ __forceinline__ unsigned xb_ld(unsigned* p)              { return __hip_atomic_load(p, __ATOMIC_RELAXED, __HIP_MEMORY_SCOPE_AGENT); }
; __device__ __forceinline__ unsigned xb_add(unsigned* p, unsigned v) { return __hip_atomic_fetch_add(p, v, __ATOMIC_RELAXED, __HIP_MEMORY_SCOPE_AGENT); }
; #define XB_SPIN(cond, bar) do { unsigned _sp = 0; while (cond) { __builtin_amdgcn_s_sleep(1); \
;     if ((++_sp & 255u) == 0u) { if (xb_ld(&(bar)[XB_TMO])) break; if (_sp > XB_SPIN_CAP) { atomicAdd(&(bar)[XB_TMO], 1u); break; } } } } while (0)
; __device__ __forceinline__ void xcd_barrier(const XcdBarrier& b) {
;     ...
;         const unsigned old = xb_add(&bar[XB_XSUB(b.x)], 1u);
;         const unsigned gen = old / nloc;
;         if (old + 1u == (gen + 1u) * nloc) {
;             __builtin_amdgcn_fence(__ATOMIC_RELEASE, "agent");
;             asm volatile("s_waitcnt vmcnt(0)" ::: "memory");
;             const unsigned og = xb_add(&bar[XB_TOP], 1u);
;             const unsigned tg = og / nx;
;             if (og + 1u == (tg + 1u) * nx) xb_add(&bar[XB_TOPGEN], 1u);
;             else XB_SPIN(xb_ld(&bar[XB_TOPGEN]) == tg, bar);
.LBB0_221:
	s_or_b64 exec, exec, s[12:13]
	v_cvt_f32_u32_e32 v6, v2
	s_waitcnt vmcnt(0)
	v_readfirstlane_b32 s11, v4
	v_sub_u32_e32 v4, 0, v2
	s_add_u32 s10, s4, 0x3500
	v_rcp_iflag_f32_e32 v6, v6
	v_add_u32_e32 v3, s11, v3
	v_add_u32_e32 v7, 1, v3
	s_addc_u32 s11, s5, 0
	v_mul_f32_e32 v6, 0x4f7ffffe, v6
	v_cvt_u32_f32_e32 v6, v6
	s_mov_b64 s[14:15], -1
	v_mul_lo_u32 v4, v4, v6
	v_mul_hi_u32 v4, v6, v4
	v_add_u32_e32 v4, v6, v4
	v_mul_hi_u32 v4, v3, v4
	v_mul_lo_u32 v6, v4, v2
	v_sub_u32_e32 v3, v3, v6
	v_add_u32_e32 v8, 1, v4
	v_sub_u32_e32 v6, v3, v2
	v_cmp_ge_u32_e32 vcc, v3, v2
	s_nop 1
	v_cndmask_b32_e32 v4, v4, v8, vcc
	v_cndmask_b32_e32 v3, v3, v6, vcc
	v_add_u32_e32 v6, 1, v4
	v_cmp_ge_u32_e32 vcc, v3, v2
	s_nop 1
	v_cndmask_b32_e32 v4, v4, v6, vcc
	v_mul_lo_u32 v3, v2, v4
	v_add_u32_e32 v2, v3, v2
	v_cmp_ne_u32_e32 vcc, v7, v2
	v_mov_b64_e32 v[2:3], s[10:11]
	s_and_b64 s[98:99], vcc, exec
	s_and_saveexec_b64 s[12:13], vcc
	s_cbranch_execz .LBB0_233
	global_load_dword v2, v5, s[10:11] sc1
	s_mov_b64 s[20:21], 0
	s_waitcnt vmcnt(0)
	v_cmp_eq_u32_e32 vcc, v2, v4
	s_and_saveexec_b64 s[16:17], vcc
	s_cbranch_execz .LBB0_232
	s_add_u32 s14, s4, 0x200
	s_addc_u32 s15, s5, 0
	s_mov_b32 s30, 1
	s_mov_b64 s[4:5], 0
	s_branch .LBB0_225

; __device__ __forceinline__ unsigned xb_add(unsigned* p, unsigned v) { return __hip_atomic_fetch_add(p, v, __ATOMIC_RELAXED, __HIP_MEMORY_SCOPE_AGENT); }
; __device__ __forceinline__ void xcd_barrier(const XcdBarrier& b) {
;     ...
;             __builtin_amdgcn_fence(__ATOMIC_ACQUIRE, "agent");
;             xb_add(&bar[XB_XGEN(b.x)], 1u);
.Lxb_notlast_2:
	s_mov_b64 s[4:5], exec
	v_mbcnt_lo_u32_b32 v2, s4, 0
	v_mbcnt_hi_u32_b32 v2, s5, v2
	v_cmp_eq_u32_e32 vcc, 0, v2
	s_waitcnt vmcnt(0)
	buffer_inv sc1
	s_and_saveexec_b64 s[10:11], vcc
	s_cbranch_execz .LBB0_237
	s_bcnt1_i32_b64 s4, s[4:5]
	v_mov_b32_e32 v2, s4
	v_mov_b32_e32 v3, 0x2000

; __device__ __forceinline__ unsigned xb_ld(unsigned* p)              { return __hip_atomic_load(p, __ATOMIC_RELAXED, __HIP_MEMORY_SCOPE_AGENT); }
; __device__ __forceinline__ unsigned xb_add(unsigned* p, unsigned v) { return __hip_atomic_fetch_add(p, v, __ATOMIC_RELAXED, __HIP_MEMORY_SCOPE_AGENT); }
; #define XB_SPIN(cond, bar) do { unsigned _sp = 0; while (cond) { __builtin_amdgcn_s_sleep(1); \
;     if ((++_sp & 255u) == 0u) { if (xb_ld(&(bar)[XB_TMO])) break; if (_sp > XB_SPIN_CAP) { atomicAdd(&(bar)[XB_TMO], 1u); break; } } } } while (0)
; __device__ __forceinline__ void xcd_barrier(const XcdBarrier& b) {
;     ...
;         const unsigned old = xb_add(&bar[XB_XSUB(b.x)], 1u);
;         const unsigned gen = old / nloc;
;         if (old + 1u == (gen + 1u) * nloc) {
;             __builtin_amdgcn_fence(__ATOMIC_RELEASE, "agent");
;             asm volatile("s_waitcnt vmcnt(0)" ::: "memory");
;             const unsigned og = xb_add(&bar[XB_TOP], 1u);
;             const unsigned tg = og / nx;
;             if (og + 1u == (tg + 1u) * nx) xb_add(&bar[XB_TOPGEN], 1u);
;             else XB_SPIN(xb_ld(&bar[XB_TOPGEN]) == tg, bar);
.LBB0_318:
	s_or_b64 exec, exec, s[12:13]
	s_waitcnt vmcnt(0)
	v_readfirstlane_b32 s10, v4
	v_cvt_f32_u32_e32 v4, v2
	v_sub_u32_e32 v6, 0, v2
	v_add_u32_e32 v3, s10, v3
	s_add_u32 s10, s4, 0x3500
	v_rcp_iflag_f32_e32 v4, v4
	s_addc_u32 s11, s5, 0
	s_mov_b64 s[14:15], -1
	v_mul_f32_e32 v4, 0x4f7ffffe, v4
	v_cvt_u32_f32_e32 v4, v4
	v_mul_lo_u32 v6, v6, v4
	v_mul_hi_u32 v6, v4, v6
	v_add_u32_e32 v4, v4, v6
	v_mul_hi_u32 v4, v3, v4
	v_mul_lo_u32 v6, v4, v2
	v_sub_u32_e32 v6, v3, v6
	v_cmp_ge_u32_e32 vcc, v6, v2
	v_add_u32_e32 v7, 1, v4
	v_add_u32_e32 v3, 1, v3
	v_cndmask_b32_e32 v4, v4, v7, vcc
	v_sub_u32_e32 v7, v6, v2
	v_cndmask_b32_e32 v6, v6, v7, vcc
	v_cmp_ge_u32_e32 vcc, v6, v2
	v_add_u32_e32 v6, 1, v4
	s_nop 0
	v_cndmask_b32_e32 v4, v4, v6, vcc
	v_mul_lo_u32 v6, v2, v4
	v_add_u32_e32 v2, v6, v2
	v_cmp_ne_u32_e32 vcc, v3, v2
	v_mov_b64_e32 v[2:3], s[10:11]
	s_and_b64 s[98:99], vcc, exec
	s_and_saveexec_b64 s[12:13], vcc
	s_cbranch_execz .LBB0_330
	global_load_dword v2, v5, s[10:11] sc1
	s_mov_b64 s[20:21], 0
	s_waitcnt vmcnt(0)
	v_cmp_eq_u32_e32 vcc, v2, v4
	s_and_saveexec_b64 s[16:17], vcc
	s_cbranch_execz .LBB0_329
	s_add_u32 s14, s4, 0x200
	s_addc_u32 s15, s5, 0
	s_mov_b32 s30, 1
	s_mov_b64 s[4:5], 0
	s_branch .LBB0_322

; __device__ __forceinline__ unsigned xb_ld(unsigned* p)              { return __hip_atomic_load(p, __ATOMIC_RELAXED, __HIP_MEMORY_SCOPE_AGENT); }
; __device__ __forceinline__ unsigned xb_add(unsigned* p, unsigned v) { return __hip_atomic_fetch_add(p, v, __ATOMIC_RELAXED, __HIP_MEMORY_SCOPE_AGENT); }
; #define XB_SPIN(cond, bar) do { unsigned _sp = 0; while (cond) { __builtin_amdgcn_s_sleep(1); \
;     if ((++_sp & 255u) == 0u) { if (xb_ld(&(bar)[XB_TMO])) break; if (_sp > XB_SPIN_CAP) { atomicAdd(&(bar)[XB_TMO], 1u); break; } } } } while (0)
; __device__ __forceinline__ void xcd_barrier(const XcdBarrier& b) {
;     ...
;         const unsigned old = xb_add(&bar[XB_XSUB(b.x)], 1u);
;         const unsigned gen = old / nloc;
;         if (old + 1u == (gen + 1u) * nloc) {
;             __builtin_amdgcn_fence(__ATOMIC_RELEASE, "agent");
;             asm volatile("s_waitcnt vmcnt(0)" ::: "memory");
;             const unsigned og = xb_add(&bar[XB_TOP], 1u);
;             const unsigned tg = og / nx;
;             if (og + 1u == (tg + 1u) * nx) xb_add(&bar[XB_TOPGEN], 1u);
;             else XB_SPIN(xb_ld(&bar[XB_TOPGEN]) == tg, bar);
.LBB0_440:
	s_or_b64 exec, exec, s[10:11]
	s_waitcnt vmcnt(0)
	v_readfirstlane_b32 s8, v4
	v_cvt_f32_u32_e32 v4, v2
	v_sub_u32_e32 v6, 0, v2
	v_add_u32_e32 v3, s8, v3
	s_add_u32 s8, s4, 0x3500
	v_rcp_iflag_f32_e32 v4, v4
	s_addc_u32 s9, s5, 0
	s_mov_b64 s[12:13], -1
	v_mul_f32_e32 v4, 0x4f7ffffe, v4
	v_cvt_u32_f32_e32 v4, v4
	v_mul_lo_u32 v6, v6, v4
	v_mul_hi_u32 v6, v4, v6
	v_add_u32_e32 v4, v4, v6
	v_mul_hi_u32 v4, v3, v4
	v_mul_lo_u32 v6, v4, v2
	v_sub_u32_e32 v6, v3, v6
	v_cmp_ge_u32_e32 vcc, v6, v2
	v_add_u32_e32 v7, 1, v4
	v_add_u32_e32 v3, 1, v3
	v_cndmask_b32_e32 v4, v4, v7, vcc
	v_sub_u32_e32 v7, v6, v2
	v_cndmask_b32_e32 v6, v6, v7, vcc
	v_cmp_ge_u32_e32 vcc, v6, v2
	v_add_u32_e32 v6, 1, v4
	s_nop 0
	v_cndmask_b32_e32 v4, v4, v6, vcc
	v_mul_lo_u32 v6, v2, v4
	v_add_u32_e32 v2, v6, v2
	v_cmp_ne_u32_e32 vcc, v3, v2
	v_mov_b64_e32 v[2:3], s[8:9]
	s_and_b64 s[98:99], vcc, exec
	s_and_saveexec_b64 s[10:11], vcc
	s_cbranch_execz .LBB0_452
	global_load_dword v2, v5, s[8:9] sc1
	s_mov_b64 s[16:17], 0
	s_waitcnt vmcnt(0)
	v_cmp_eq_u32_e32 vcc, v2, v4
	s_and_saveexec_b64 s[14:15], vcc
	s_cbranch_execz .LBB0_451
	s_add_u32 s12, s4, 0x200
	s_addc_u32 s13, s5, 0
	s_mov_b32 s26, 1
	s_mov_b64 s[4:5], 0
	s_branch .LBB0_444

; __device__ __forceinline__ unsigned xb_add(unsigned* p, unsigned v) { return __hip_atomic_fetch_add(p, v, __ATOMIC_RELAXED, __HIP_MEMORY_SCOPE_AGENT); }
; __device__ __forceinline__ void xcd_barrier(const XcdBarrier& b) {
;     ...
;             __builtin_amdgcn_fence(__ATOMIC_ACQUIRE, "agent");
;             xb_add(&bar[XB_XGEN(b.x)], 1u);
.Lxb_notlast_4:
	s_mov_b64 s[4:5], exec
	v_mbcnt_lo_u32_b32 v2, s4, 0
	v_mbcnt_hi_u32_b32 v2, s5, v2
	v_cmp_eq_u32_e32 vcc, 0, v2
	s_waitcnt vmcnt(0)
	buffer_inv sc1
	s_and_saveexec_b64 s[8:9], vcc
	s_cbranch_execz .LBB0_456
	s_bcnt1_i32_b64 s4, s[4:5]
	v_mov_b32_e32 v2, s4
	v_mov_b32_e32 v3, 0x2000

; __device__ __forceinline__ unsigned xb_ld(unsigned* p)              { return __hip_atomic_load(p, __ATOMIC_RELAXED, __HIP_MEMORY_SCOPE_AGENT); }
; __device__ __forceinline__ unsigned xb_add(unsigned* p, unsigned v) { return __hip_atomic_fetch_add(p, v, __ATOMIC_RELAXED, __HIP_MEMORY_SCOPE_AGENT); }
; #define XB_SPIN(cond, bar) do { unsigned _sp = 0; while (cond) { __builtin_amdgcn_s_sleep(1); \
;     if ((++_sp & 255u) == 0u) { if (xb_ld(&(bar)[XB_TMO])) break; if (_sp > XB_SPIN_CAP) { atomicAdd(&(bar)[XB_TMO], 1u); break; } } } } while (0)
; __device__ __forceinline__ void xcd_barrier(const XcdBarrier& b) {
;     ...
;         const unsigned old = xb_add(&bar[XB_XSUB(b.x)], 1u);
;         const unsigned gen = old / nloc;
;         if (old + 1u == (gen + 1u) * nloc) {
;             __builtin_amdgcn_fence(__ATOMIC_RELEASE, "agent");
;             asm volatile("s_waitcnt vmcnt(0)" ::: "memory");
;             const unsigned og = xb_add(&bar[XB_TOP], 1u);
;             const unsigned tg = og / nx;
;             if (og + 1u == (tg + 1u) * nx) xb_add(&bar[XB_TOPGEN], 1u);
;             else XB_SPIN(xb_ld(&bar[XB_TOPGEN]) == tg, bar);
.LBB0_797:
	s_or_b64 exec, exec, s[12:13]
	s_waitcnt vmcnt(0)
	v_readfirstlane_b32 s10, v4
	v_cvt_f32_u32_e32 v4, v2
	v_sub_u32_e32 v6, 0, v2
	v_add_u32_e32 v3, s10, v3
	s_add_u32 s10, s4, 0x3500
	v_rcp_iflag_f32_e32 v4, v4
	s_addc_u32 s11, s5, 0
	s_mov_b64 s[14:15], -1
	v_mul_f32_e32 v4, 0x4f7ffffe, v4
	v_cvt_u32_f32_e32 v4, v4
	v_mul_lo_u32 v6, v6, v4
	v_mul_hi_u32 v6, v4, v6
	v_add_u32_e32 v4, v4, v6
	v_mul_hi_u32 v4, v3, v4
	v_mul_lo_u32 v6, v4, v2
	v_sub_u32_e32 v6, v3, v6
	v_cmp_ge_u32_e32 vcc, v6, v2
	v_add_u32_e32 v7, 1, v4
	v_add_u32_e32 v3, 1, v3
	v_cndmask_b32_e32 v4, v4, v7, vcc
	v_sub_u32_e32 v7, v6, v2
	v_cndmask_b32_e32 v6, v6, v7, vcc
	v_cmp_ge_u32_e32 vcc, v6, v2
	v_add_u32_e32 v6, 1, v4
	s_nop 0
	v_cndmask_b32_e32 v4, v4, v6, vcc
	v_mul_lo_u32 v6, v2, v4
	v_add_u32_e32 v2, v6, v2
	v_cmp_ne_u32_e32 vcc, v3, v2
	v_mov_b64_e32 v[2:3], s[10:11]
	s_and_b64 s[98:99], vcc, exec
	s_and_saveexec_b64 s[12:13], vcc
	s_cbranch_execz .LBB0_809
	global_load_dword v2, v5, s[10:11] sc1
	s_mov_b64 s[20:21], 0
	s_waitcnt vmcnt(0)
	v_cmp_eq_u32_e32 vcc, v2, v4
	s_and_saveexec_b64 s[16:17], vcc
	s_cbranch_execz .LBB0_808
	s_add_u32 s14, s4, 0x200
	s_addc_u32 s15, s5, 0
	s_mov_b32 s34, 1
	s_mov_b64 s[4:5], 0
	s_branch .LBB0_801

; __device__ __forceinline__ unsigned xb_ld(unsigned* p)              { return __hip_atomic_load(p, __ATOMIC_RELAXED, __HIP_MEMORY_SCOPE_AGENT); }
; __device__ __forceinline__ unsigned xb_add(unsigned* p, unsigned v) { return __hip_atomic_fetch_add(p, v, __ATOMIC_RELAXED, __HIP_MEMORY_SCOPE_AGENT); }
; #define XB_SPIN(cond, bar) do { unsigned _sp = 0; while (cond) { __builtin_amdgcn_s_sleep(1); \
;     if ((++_sp & 255u) == 0u) { if (xb_ld(&(bar)[XB_TMO])) break; if (_sp > XB_SPIN_CAP) { atomicAdd(&(bar)[XB_TMO], 1u); break; } } } } while (0)
; __device__ __forceinline__ void xcd_barrier(const XcdBarrier& b) {
;     ...
;         const unsigned old = xb_add(&bar[XB_XSUB(b.x)], 1u);
;         const unsigned gen = old / nloc;
;         if (old + 1u == (gen + 1u) * nloc) {
;             __builtin_amdgcn_fence(__ATOMIC_RELEASE, "agent");
;             asm volatile("s_waitcnt vmcnt(0)" ::: "memory");
;             const unsigned og = xb_add(&bar[XB_TOP], 1u);
;             const unsigned tg = og / nx;
;             if (og + 1u == (tg + 1u) * nx) xb_add(&bar[XB_TOPGEN], 1u);
;             else XB_SPIN(xb_ld(&bar[XB_TOPGEN]) == tg, bar);
.LBB0_1049:
	s_or_b64 exec, exec, s[10:11]
	s_waitcnt vmcnt(0)
	v_readfirstlane_b32 s8, v4
	v_cvt_f32_u32_e32 v4, v2
	v_sub_u32_e32 v6, 0, v2
	v_add_u32_e32 v3, s8, v3
	s_add_u32 s8, s4, 0x3500
	v_rcp_iflag_f32_e32 v4, v4
	s_addc_u32 s9, s5, 0
	s_mov_b64 s[12:13], -1
	v_mul_f32_e32 v4, 0x4f7ffffe, v4
	v_cvt_u32_f32_e32 v4, v4
	v_mul_lo_u32 v6, v6, v4
	v_mul_hi_u32 v6, v4, v6
	v_add_u32_e32 v4, v4, v6
	v_mul_hi_u32 v4, v3, v4
	v_mul_lo_u32 v6, v4, v2
	v_sub_u32_e32 v6, v3, v6
	v_cmp_ge_u32_e32 vcc, v6, v2
	v_add_u32_e32 v7, 1, v4
	v_add_u32_e32 v3, 1, v3
	v_cndmask_b32_e32 v4, v4, v7, vcc
	v_sub_u32_e32 v7, v6, v2
	v_cndmask_b32_e32 v6, v6, v7, vcc
	v_cmp_ge_u32_e32 vcc, v6, v2
	v_add_u32_e32 v6, 1, v4
	s_nop 0
	v_cndmask_b32_e32 v4, v4, v6, vcc
	v_mul_lo_u32 v6, v2, v4
	v_add_u32_e32 v2, v6, v2
	v_cmp_ne_u32_e32 vcc, v3, v2
	v_mov_b64_e32 v[2:3], s[8:9]
	s_and_b64 s[98:99], vcc, exec
	s_and_saveexec_b64 s[10:11], vcc
	s_cbranch_execz .LBB0_1061
	global_load_dword v2, v5, s[8:9] sc1
	s_mov_b64 s[16:17], 0
	s_waitcnt vmcnt(0)
	v_cmp_eq_u32_e32 vcc, v2, v4
	s_and_saveexec_b64 s[14:15], vcc
	s_cbranch_execz .LBB0_1060
	s_add_u32 s12, s4, 0x200
	s_addc_u32 s13, s5, 0
	s_mov_b32 s27, 1
	s_mov_b64 s[4:5], 0
	s_branch .LBB0_1053

; #define LAS __attribute__((address_space(3)))
; __global__ __launch_bounds__(512) void fwd_megakernel(P p_arg) {
;     P p = p_arg;
;     extern __shared__ __attribute__((aligned(16))) unsigned char shm[];
;     LAS unsigned char* lds = (LAS unsigned char*)shm;
;     Ctx c; c.tid = threadIdx.x; c.wv = threadIdx.x >> 6; c.lane = threadIdx.x & 63; c.G = gridDim.x; c.bid = blockIdx.x; c.lds = lds; c.seg = p.ws + OFF_SEG;
;     volatile LAS unsigned* st = (volatile LAS unsigned*)(lds + LDS_BYTES - 16);
	.amdhsa_kernel _Z14fwd_megakernel1P
		.amdhsa_group_segment_fixed_size 0
		.amdhsa_private_segment_fixed_size 0
		.amdhsa_kernarg_size 520
		.amdhsa_user_sgpr_count 2
		.amdhsa_user_sgpr_dispatch_ptr 0
		.amdhsa_user_sgpr_queue_ptr 0
		.amdhsa_user_sgpr_kernarg_segment_ptr 1
		.amdhsa_user_sgpr_dispatch_id 0
		.amdhsa_user_sgpr_kernarg_preload_length 0
		.amdhsa_user_sgpr_kernarg_preload_offset 0
		.amdhsa_user_sgpr_private_segment_size 0
		.amdhsa_uses_dynamic_stack 0
		.amdhsa_enable_private_segment 0
		.amdhsa_system_sgpr_workgroup_id_x 1
		.amdhsa_system_sgpr_workgroup_id_y 0
		.amdhsa_system_sgpr_workgroup_id_z 0
		.amdhsa_system_sgpr_workgroup_info 0
		.amdhsa_system_vgpr_workitem_id 0
		.amdhsa_next_free_vgpr 256
		.amdhsa_next_free_sgpr 102
		.amdhsa_accum_offset 256
		.amdhsa_reserve_vcc 1
		.amdhsa_float_round_mode_32 0
		.amdhsa_float_round_mode_16_64 0
		.amdhsa_float_denorm_mode_32 3
		.amdhsa_float_denorm_mode_16_64 3
		.amdhsa_dx10_clamp 1
		.amdhsa_ieee_mode 1
		.amdhsa_fp16_overflow 0
		.amdhsa_tg_split 0
		.amdhsa_exception_fp_ieee_invalid_op 0
		.amdhsa_exception_fp_denorm_src 0
		.amdhsa_exception_fp_ieee_div_zero 0
		.amdhsa_exception_fp_ieee_overflow 0
		.amdhsa_exception_fp_ieee_underflow 0
		.amdhsa_exception_fp_ieee_inexact 0
		.amdhsa_exception_int_div_zero 0
	.end_amdhsa_kernel

amdhsa.kernels:
  - .agpr_count:     0
    .args:
      - .offset:         0
        .size:           264
        .value_kind:     by_value
      - .offset:         264
        .size:           4
        .value_kind:     hidden_block_count_x
      - .offset:         268
        .size:           4
        .value_kind:     hidden_block_count_y
      - .offset:         272
        .size:           4
        .value_kind:     hidden_block_count_z
      - .offset:         276
        .size:           2
        .value_kind:     hidden_group_size_x
      - .offset:         278
        .size:           2
        .value_kind:     hidden_group_size_y
      - .offset:         280
        .size:           2
        .value_kind:     hidden_group_size_z
      - .offset:         282
        .size:           2
        .value_kind:     hidden_remainder_x
      - .offset:         284
        .size:           2
        .value_kind:     hidden_remainder_y
      - .offset:         286
        .size:           2
        .value_kind:     hidden_remainder_z
      - .offset:         304
        .size:           8
        .value_kind:     hidden_global_offset_x
      - .offset:         312
        .size:           8
        .value_kind:     hidden_global_offset_y
      - .offset:         320
        .size:           8
        .value_kind:     hidden_global_offset_z
      - .offset:         328
        .size:           2
        .value_kind:     hidden_grid_dims
      - .offset:         384
        .size:           4
        .value_kind:     hidden_dynamic_lds_size
    .group_segment_fixed_size: 0
    .kernarg_segment_align: 8
    .kernarg_segment_size: 520
    .language:       OpenCL C
    .language_version:
      - 2
      - 0
    .max_flat_workgroup_size: 512
    .name:           _Z14fwd_megakernel1P
    .private_segment_fixed_size: 0
    .sgpr_count:     108
    .sgpr_spill_count: 63
    .symbol:         _Z14fwd_megakernel1P.kd
    .uniform_work_group_size: 1
    .uses_dynamic_stack: false
    .vgpr_count:     256
    .vgpr_spill_count: 0
    .wavefront_size: 64
